# v019 plus select find_bin<12>: per-lane 64-bin sum by 16 rotated conflict-free ds_read_b128 instead of 32 serialized ds_read_b32 pairs
# baseline (speedup 1.0000x reference)
; #define LAS __attribute__((address_space(3)))
; template <int BITS> __device__ __forceinline__ unsigned find_bin(const LAS unsigned* hist, unsigned& k, int lane) {
;     constexpr int NBIN = 1 << BITS, PER = NBIN / 64;
;     unsigned s = 0;
; #pragma unroll 8
;     for (int j = 0; j < PER; ++j) s += hist[PER * lane + ((j + lane) & (PER - 1))];
;     const unsigned incl = suffix_incl(s, lane), excl = incl - s;
.LBB0_742:
	v_and_b32_e32 v0, 15, v116
	v_lshlrev_b32_e32 v0, 4, v0
	s_movk_i32 s4, 0xff
	v_mov_b32_e32 v2, 0
	v_and_or_b32 v3, v0, s4, v134
	ds_read_b128 v[4:7], v3
	v_add_u32_e32 v3, 16, v0
	v_and_or_b32 v3, v3, s4, v134
	ds_read_b128 v[8:11], v3
	v_add_u32_e32 v3, 32, v0
	v_and_or_b32 v3, v3, s4, v134
	ds_read_b128 v[12:15], v3
	v_add_u32_e32 v3, 48, v0
	v_and_or_b32 v3, v3, s4, v134
	ds_read_b128 v[16:19], v3
	s_waitcnt lgkmcnt(3)
	v_add3_u32 v2, v4, v2, v5
	v_add3_u32 v2, v6, v2, v7
	v_add_u32_e32 v3, 64, v0
	v_and_or_b32 v3, v3, s4, v134
	ds_read_b128 v[4:7], v3
	s_waitcnt lgkmcnt(3)
	v_add3_u32 v2, v8, v2, v9
	v_add3_u32 v2, v10, v2, v11
	v_add_u32_e32 v3, 80, v0
	v_and_or_b32 v3, v3, s4, v134
	ds_read_b128 v[8:11], v3
	s_waitcnt lgkmcnt(3)
	v_add3_u32 v2, v12, v2, v13
	v_add3_u32 v2, v14, v2, v15
	v_add_u32_e32 v3, 96, v0
	v_and_or_b32 v3, v3, s4, v134
	ds_read_b128 v[12:15], v3
	s_waitcnt lgkmcnt(3)
	v_add3_u32 v2, v16, v2, v17
	v_add3_u32 v2, v18, v2, v19
	v_add_u32_e32 v3, 112, v0
	v_and_or_b32 v3, v3, s4, v134
	ds_read_b128 v[16:19], v3
	s_waitcnt lgkmcnt(3)
	v_add3_u32 v2, v4, v2, v5
	v_add3_u32 v2, v6, v2, v7
	v_add_u32_e32 v3, 128, v0
	v_and_or_b32 v3, v3, s4, v134
	ds_read_b128 v[4:7], v3
	s_waitcnt lgkmcnt(3)
	v_add3_u32 v2, v8, v2, v9
	v_add3_u32 v2, v10, v2, v11
	v_add_u32_e32 v3, 144, v0
	v_and_or_b32 v3, v3, s4, v134
	ds_read_b128 v[8:11], v3
	s_waitcnt lgkmcnt(3)
	v_add3_u32 v2, v12, v2, v13
	v_add3_u32 v2, v14, v2, v15
	v_add_u32_e32 v3, 160, v0
	v_and_or_b32 v3, v3, s4, v134
	ds_read_b128 v[12:15], v3
	s_waitcnt lgkmcnt(3)
	v_add3_u32 v2, v16, v2, v17
	v_add3_u32 v2, v18, v2, v19
	v_add_u32_e32 v3, 176, v0
	v_and_or_b32 v3, v3, s4, v134
	ds_read_b128 v[16:19], v3
	s_waitcnt lgkmcnt(3)
	v_add3_u32 v2, v4, v2, v5
	v_add3_u32 v2, v6, v2, v7
	v_add_u32_e32 v3, 192, v0
	v_and_or_b32 v3, v3, s4, v134
	ds_read_b128 v[4:7], v3
	s_waitcnt lgkmcnt(3)
	v_add3_u32 v2, v8, v2, v9
	v_add3_u32 v2, v10, v2, v11
	v_add_u32_e32 v3, 208, v0
	v_and_or_b32 v3, v3, s4, v134
	ds_read_b128 v[8:11], v3
	s_waitcnt lgkmcnt(3)
	v_add3_u32 v2, v12, v2, v13
	v_add3_u32 v2, v14, v2, v15
	v_add_u32_e32 v3, 224, v0
	v_and_or_b32 v3, v3, s4, v134
	ds_read_b128 v[12:15], v3
	s_waitcnt lgkmcnt(3)
	v_add3_u32 v2, v16, v2, v17
	v_add3_u32 v2, v18, v2, v19
	v_add_u32_e32 v3, 240, v0
	v_and_or_b32 v3, v3, s4, v134
	ds_read_b128 v[16:19], v3
	s_waitcnt lgkmcnt(3)
	v_add3_u32 v2, v4, v2, v5
	v_add3_u32 v2, v6, v2, v7
	s_waitcnt lgkmcnt(2)
	v_add3_u32 v2, v8, v2, v9
	v_add3_u32 v2, v10, v2, v11
	s_waitcnt lgkmcnt(1)
	v_add3_u32 v2, v12, v2, v13
	v_add3_u32 v2, v14, v2, v15
	s_waitcnt lgkmcnt(0)
	v_add3_u32 v2, v16, v2, v17
	v_add3_u32 v2, v18, v2, v19
